# LayerNorm gamma/beta loads back to the default cache policy (re-read every iteration: L1 hits); row loads stay nt
# speedup vs baseline: 1.0152x; 1.0073x over previous
.LBB0_1552:
	v_add_co_u32_e32 v0, vcc, 0xffff8400, v138
	s_nop 1
	v_addc_co_u32_e32 v1, vcc, -1, v139, vcc
	v_add_co_u32_e32 v2, vcc, 0xffff8800, v138
	s_nop 1
	v_addc_co_u32_e32 v3, vcc, -1, v139, vcc
	s_waitcnt vmcnt(0)
	global_load_dwordx4 v[84:87], v[0:1], off nt
	global_load_dwordx4 v[48:51], v[2:3], off nt
	v_add_co_u32_e32 v0, vcc, 0xffff8c00, v138
	s_waitcnt vmcnt(0) lgkmcnt(0)
	v_add_f32_e32 v128, v84, v85
	v_addc_co_u32_e32 v1, vcc, -1, v139, vcc
	v_add_co_u32_e32 v2, vcc, 0xffff9000, v138
	v_add_f32_e32 v129, v86, v87
	s_nop 0
	v_addc_co_u32_e32 v3, vcc, -1, v139, vcc
	v_add_co_u32_e32 v4, vcc, 0xffff9400, v138
	global_load_dwordx4 v[20:23], v[0:1], off nt
	s_nop 0
	global_load_dwordx4 v[0:3], v[2:3], off nt
	v_addc_co_u32_e32 v5, vcc, -1, v139, vcc
	v_add_co_u32_e32 v6, vcc, 0xffff9800, v138
	v_add_f32_e32 v128, v128, v129
	s_nop 0
	v_addc_co_u32_e32 v7, vcc, -1, v139, vcc
	global_load_dwordx4 v[92:95], v[4:5], off nt
	global_load_dwordx4 v[56:59], v[6:7], off nt
	v_add_co_u32_e32 v4, vcc, 0xffff9c00, v138
	v_add_f32_e32 v129, v48, v49
	s_nop 0
	v_addc_co_u32_e32 v5, vcc, -1, v139, vcc
	v_add_co_u32_e32 v6, vcc, 0xffffa000, v138
	v_add_f32_e32 v130, v50, v51
	s_nop 0
	v_addc_co_u32_e32 v7, vcc, -1, v139, vcc
	v_add_co_u32_e32 v8, vcc, 0xffffa400, v138
	global_load_dwordx4 v[28:31], v[4:5], off nt
	s_nop 0
	global_load_dwordx4 v[4:7], v[6:7], off nt
	v_addc_co_u32_e32 v9, vcc, -1, v139, vcc
	v_add_co_u32_e32 v10, vcc, 0xffffa800, v138
	v_add_f32_e32 v128, 0, v128
	s_nop 0
	v_addc_co_u32_e32 v11, vcc, -1, v139, vcc
	global_load_dwordx4 v[100:103], v[8:9], off nt
	global_load_dwordx4 v[64:67], v[10:11], off nt
	v_add_co_u32_e32 v8, vcc, 0xffffac00, v138
	v_add_f32_e32 v129, v129, v130
	s_nop 0
	v_addc_co_u32_e32 v9, vcc, -1, v139, vcc
	v_add_co_u32_e32 v10, vcc, 0xffffb000, v138
	v_add_f32_e32 v128, v128, v129
	s_nop 0
	v_addc_co_u32_e32 v11, vcc, -1, v139, vcc
	v_add_co_u32_e32 v12, vcc, 0xffffb400, v138
	global_load_dwordx4 v[36:39], v[8:9], off nt
	s_nop 0
	global_load_dwordx4 v[8:11], v[10:11], off nt
	v_addc_co_u32_e32 v13, vcc, -1, v139, vcc
	v_add_co_u32_e32 v14, vcc, 0xffffb800, v138
	s_waitcnt vmcnt(0) lgkmcnt(0)
	v_add_f32_e32 v129, v20, v21
	v_addc_co_u32_e32 v15, vcc, -1, v139, vcc
	global_load_dwordx4 v[108:111], v[12:13], off nt
	global_load_dwordx4 v[76:79], v[14:15], off nt
	v_add_co_u32_e32 v12, vcc, 0xffffbc00, v138
	v_add_f32_e32 v130, v22, v23
	s_nop 0
	v_addc_co_u32_e32 v13, vcc, -1, v139, vcc
	v_add_co_u32_e32 v14, vcc, 0xffffc000, v138
	v_add_f32_e32 v129, v129, v130
	s_nop 0
	v_addc_co_u32_e32 v15, vcc, -1, v139, vcc
	v_add_co_u32_e32 v16, vcc, 0xffffc400, v138
	global_load_dwordx4 v[44:47], v[12:13], off nt
	s_nop 0
	global_load_dwordx4 v[12:15], v[14:15], off nt
	v_addc_co_u32_e32 v17, vcc, -1, v139, vcc
	v_add_co_u32_e32 v18, vcc, 0xffffc800, v138
	v_add_f32_e32 v128, v128, v129
	s_nop 0
	v_addc_co_u32_e32 v19, vcc, -1, v139, vcc
	global_load_dwordx4 v[112:115], v[16:17], off nt
	global_load_dwordx4 v[80:83], v[18:19], off nt
	v_add_co_u32_e32 v16, vcc, 0xffffcc00, v138
	v_add_f32_e32 v129, v0, v1
	s_nop 0
	v_addc_co_u32_e32 v17, vcc, -1, v139, vcc
	v_add_co_u32_e32 v18, vcc, 0xffffd000, v138
	v_add_f32_e32 v130, v2, v3
	s_nop 0
	v_addc_co_u32_e32 v19, vcc, -1, v139, vcc
	v_add_co_u32_e32 v24, vcc, 0xffffd400, v138
	global_load_dwordx4 v[52:55], v[16:17], off nt
	s_nop 0
	global_load_dwordx4 v[16:19], v[18:19], off nt
	v_addc_co_u32_e32 v25, vcc, -1, v139, vcc
	v_add_co_u32_e32 v26, vcc, 0xffffd800, v138
	v_add_f32_e32 v129, v129, v130
	s_nop 0
	v_addc_co_u32_e32 v27, vcc, -1, v139, vcc
	global_load_dwordx4 v[116:119], v[24:25], off nt
	global_load_dwordx4 v[88:91], v[26:27], off nt
	v_add_co_u32_e32 v24, vcc, 0xffffdc00, v138
	v_add_f32_e32 v128, v128, v129
	s_nop 0
	v_addc_co_u32_e32 v25, vcc, -1, v139, vcc
	v_add_co_u32_e32 v26, vcc, 0xffffe000, v138
	v_add_f32_e32 v129, v92, v93
	s_nop 0
	v_addc_co_u32_e32 v27, vcc, -1, v139, vcc
	v_add_co_u32_e32 v32, vcc, 0xffffe400, v138
	global_load_dwordx4 v[60:63], v[24:25], off nt
	s_nop 0
	global_load_dwordx4 v[24:27], v[26:27], off nt
	v_addc_co_u32_e32 v33, vcc, -1, v139, vcc
	v_add_co_u32_e32 v34, vcc, s46, v138
	v_add_f32_e32 v130, v94, v95
	s_nop 0
	v_addc_co_u32_e32 v35, vcc, -1, v139, vcc
	global_load_dwordx4 v[120:123], v[32:33], off nt
	global_load_dwordx4 v[96:99], v[34:35], off nt
	v_add_co_u32_e32 v32, vcc, 0xffffec00, v138
	v_add_f32_e32 v129, v129, v130
	s_nop 0
	v_addc_co_u32_e32 v33, vcc, -1, v139, vcc
	v_add_co_u32_e32 v34, vcc, 0xfffff000, v138
	v_add_f32_e32 v130, v56, v57
	s_nop 0
	v_addc_co_u32_e32 v35, vcc, -1, v139, vcc
	global_load_dwordx4 v[68:71], v[32:33], off nt
	s_nop 0
	global_load_dwordx4 v[32:35], v[34:35], off nt
	v_add_co_u32_e32 v40, vcc, 0xfffff400, v138
	v_add_f32_e32 v131, v58, v59
	s_nop 0
	v_addc_co_u32_e32 v41, vcc, -1, v139, vcc
	v_add_co_u32_e32 v42, vcc, 0xfffff800, v138
	v_add_f32_e32 v129, 0, v129
	s_nop 0
	v_addc_co_u32_e32 v43, vcc, -1, v139, vcc
	global_load_dwordx4 v[124:127], v[40:41], off nt
	global_load_dwordx4 v[104:107], v[42:43], off nt
	v_add_co_u32_e32 v40, vcc, s76, v138
	v_add_f32_e32 v130, v130, v131
	s_nop 0
	v_addc_co_u32_e32 v41, vcc, -1, v139, vcc
	global_load_dwordx4 v[72:75], v[40:41], off nt
	s_nop 0
	global_load_dwordx4 v[40:43], v[138:139], off nt
	v_add_f32_e32 v129, v129, v130
	v_add_f32_e32 v130, v28, v29
	v_add_f32_e32 v131, v30, v31
	v_add_f32_e32 v130, v130, v131
	v_add_f32_e32 v129, v129, v130
	v_add_f32_e32 v130, v4, v5
	v_add_f32_e32 v131, v6, v7
	v_add_f32_e32 v130, v130, v131
	v_add_f32_e32 v129, v129, v130
	v_add_f32_e32 v130, v100, v101
	v_add_f32_e32 v131, v102, v103
	v_add_f32_e32 v130, v130, v131
	v_add_f32_e32 v131, v64, v65
	v_add_f32_e32 v132, v66, v67
	v_add_f32_e32 v130, 0, v130
	v_add_f32_e32 v131, v131, v132
	v_add_f32_e32 v130, v130, v131
	v_add_f32_e32 v131, v36, v37
	v_add_f32_e32 v132, v38, v39
	v_add_f32_e32 v131, v131, v132
	v_add_f32_e32 v130, v130, v131
	v_add_f32_e32 v131, v8, v9
	v_add_f32_e32 v132, v10, v11
	v_add_f32_e32 v131, v131, v132
	v_add_f32_e32 v130, v130, v131
	s_waitcnt vmcnt(0) lgkmcnt(0)
	v_add_f32_e32 v131, v108, v109
	v_add_f32_e32 v132, v110, v111
	v_add_f32_e32 v131, v131, v132
	v_add_f32_e32 v132, v76, v77
	v_add_f32_e32 v133, v78, v79
	v_add_f32_e32 v131, 0, v131
	v_add_f32_e32 v132, v132, v133
	v_add_f32_e32 v131, v131, v132
	v_add_f32_e32 v132, v44, v45
	v_add_f32_e32 v133, v46, v47
	v_add_f32_e32 v132, v132, v133
	v_add_f32_e32 v131, v131, v132
	v_add_f32_e32 v132, v12, v13
	v_add_f32_e32 v133, v14, v15
	v_add_f32_e32 v132, v132, v133
	v_add_f32_e32 v131, v131, v132
	v_add_f32_e32 v132, v112, v113
	v_add_f32_e32 v133, v114, v115
	v_add_f32_e32 v132, v132, v133
	v_add_f32_e32 v133, v80, v81
	v_add_f32_e32 v140, v82, v83
	v_add_f32_e32 v132, 0, v132
	v_add_f32_e32 v133, v133, v140
	v_add_f32_e32 v132, v132, v133
	v_add_f32_e32 v133, v52, v53
	v_add_f32_e32 v140, v54, v55
	v_add_f32_e32 v133, v133, v140
	v_add_f32_e32 v132, v132, v133
	v_add_f32_e32 v133, v16, v17
	v_add_f32_e32 v140, v18, v19
	v_add_f32_e32 v133, v133, v140
	v_add_f32_e32 v132, v132, v133
	v_add_f32_e32 v133, v116, v117
	v_add_f32_e32 v140, v118, v119
	v_add_f32_e32 v133, v133, v140
	v_add_f32_e32 v140, v88, v89
	v_add_f32_e32 v141, v90, v91
	v_add_f32_e32 v133, 0, v133
	v_add_f32_e32 v140, v140, v141
	v_add_f32_e32 v133, v133, v140
	v_add_f32_e32 v140, v60, v61
	v_add_f32_e32 v141, v62, v63
	v_add_f32_e32 v140, v140, v141
	v_add_f32_e32 v133, v133, v140
	v_add_f32_e32 v140, v24, v25
	v_add_f32_e32 v141, v26, v27
	v_add_f32_e32 v140, v140, v141
	v_add_f32_e32 v133, v133, v140
	v_add_f32_e32 v140, v120, v121
	v_add_f32_e32 v141, v122, v123
	v_add_f32_e32 v140, v140, v141
	v_add_f32_e32 v141, v96, v97
	v_add_f32_e32 v142, v98, v99
	v_add_f32_e32 v140, 0, v140
	v_add_f32_e32 v141, v141, v142
	v_add_f32_e32 v140, v140, v141
	v_add_f32_e32 v141, v68, v69
	v_add_f32_e32 v142, v70, v71
	v_add_f32_e32 v141, v141, v142
	v_add_f32_e32 v140, v140, v141
	v_add_f32_e32 v141, v32, v33
	v_add_f32_e32 v142, v34, v35
	v_add_f32_e32 v141, v141, v142
	v_add_f32_e32 v140, v140, v141
	v_add_f32_e32 v141, v124, v125
	v_add_f32_e32 v142, v126, v127
	v_add_f32_e32 v141, v141, v142
	v_add_f32_e32 v143, v104, v105
	v_add_f32_e32 v144, v106, v107
	v_add_f32_e32 v141, 0, v141
	v_add_f32_e32 v143, v143, v144
	v_add_f32_e32 v141, v141, v143
	ds_swizzle_b32 v143, v129 offset:swizzle(SWAP,1)
	ds_swizzle_b32 v142, v128 offset:swizzle(SWAP,1)
	v_add_f32_e32 v144, v72, v73
	v_add_f32_e32 v145, v74, v75
	v_add_f32_e32 v144, v144, v145
	s_waitcnt lgkmcnt(1)
	v_add_f32_e32 v129, v129, v143
	ds_swizzle_b32 v143, v129 offset:swizzle(SWAP,2)
	s_waitcnt lgkmcnt(1)
	v_add_f32_e32 v128, v128, v142
	ds_swizzle_b32 v142, v128 offset:swizzle(SWAP,2)
	v_add_f32_e32 v141, v141, v144
	v_add_f32_e32 v144, v40, v41
	s_waitcnt lgkmcnt(1)
	v_add_f32_e32 v129, v129, v143
	ds_swizzle_b32 v143, v129 offset:swizzle(SWAP,4)
	s_waitcnt lgkmcnt(1)
	v_add_f32_e32 v128, v128, v142
	ds_swizzle_b32 v142, v128 offset:swizzle(SWAP,4)
	v_add_f32_e32 v145, v42, v43
	v_add_f32_e32 v144, v144, v145
	s_waitcnt lgkmcnt(1)
	v_add_f32_e32 v129, v129, v143
	ds_swizzle_b32 v143, v129 offset:swizzle(SWAP,8)
	s_waitcnt lgkmcnt(1)
	v_add_f32_e32 v128, v128, v142
	ds_swizzle_b32 v142, v128 offset:swizzle(SWAP,8)
	v_add_f32_e32 v141, v141, v144
	ds_swizzle_b32 v144, v130 offset:swizzle(SWAP,1)
	s_waitcnt lgkmcnt(2)
	v_add_f32_e32 v129, v129, v143
	ds_swizzle_b32 v143, v129 offset:swizzle(SWAP,16)
	s_waitcnt lgkmcnt(2)
	v_add_f32_e32 v128, v128, v142
	ds_swizzle_b32 v142, v128 offset:swizzle(SWAP,16)
	s_waitcnt lgkmcnt(2)
	v_add_f32_e32 v130, v130, v144
	ds_swizzle_b32 v144, v131 offset:swizzle(SWAP,1)
	s_waitcnt lgkmcnt(2)
	v_add_f32_e32 v129, v129, v143
	v_mov_b32_e32 v143, v129
	s_waitcnt lgkmcnt(1)
	v_add_f32_e32 v128, v128, v142
	v_permlane32_swap_b32_e32 v129, v143
	v_mov_b32_e32 v142, v128
	s_waitcnt lgkmcnt(0)
	v_add_f32_e32 v131, v131, v144
	v_add_f32_e32 v129, v129, v143
	ds_swizzle_b32 v143, v132 offset:swizzle(SWAP,1)
	v_permlane32_swap_b32_e32 v128, v142
	ds_swizzle_b32 v144, v131 offset:swizzle(SWAP,2)
	v_add_f32_e32 v128, v128, v142
	ds_swizzle_b32 v142, v130 offset:swizzle(SWAP,2)
	s_waitcnt lgkmcnt(2)
	v_add_f32_e32 v132, v132, v143
	ds_swizzle_b32 v143, v132 offset:swizzle(SWAP,2)
	s_waitcnt lgkmcnt(2)
	v_add_f32_e32 v131, v131, v144
	ds_swizzle_b32 v144, v131 offset:swizzle(SWAP,4)
	s_waitcnt lgkmcnt(2)
	v_add_f32_e32 v130, v130, v142
	ds_swizzle_b32 v142, v130 offset:swizzle(SWAP,4)
	s_waitcnt lgkmcnt(2)
	v_add_f32_e32 v132, v132, v143
	ds_swizzle_b32 v143, v132 offset:swizzle(SWAP,4)
	s_waitcnt lgkmcnt(2)
	v_add_f32_e32 v131, v131, v144
	ds_swizzle_b32 v144, v131 offset:swizzle(SWAP,8)
	s_waitcnt lgkmcnt(2)
	v_add_f32_e32 v130, v130, v142
	ds_swizzle_b32 v142, v130 offset:swizzle(SWAP,8)
	s_waitcnt lgkmcnt(2)
	v_add_f32_e32 v132, v132, v143
	ds_swizzle_b32 v143, v132 offset:swizzle(SWAP,8)
	s_waitcnt lgkmcnt(2)
	v_add_f32_e32 v131, v131, v144
	ds_swizzle_b32 v144, v131 offset:swizzle(SWAP,16)
	s_waitcnt lgkmcnt(2)
	v_add_f32_e32 v130, v130, v142
	ds_swizzle_b32 v142, v130 offset:swizzle(SWAP,16)
	s_waitcnt lgkmcnt(2)
	v_add_f32_e32 v132, v132, v143
	ds_swizzle_b32 v143, v132 offset:swizzle(SWAP,16)
	s_waitcnt lgkmcnt(2)
	v_add_f32_e32 v131, v131, v144
	ds_swizzle_b32 v144, v133 offset:swizzle(SWAP,1)
	s_waitcnt lgkmcnt(2)
	v_add_f32_e32 v130, v130, v142
	v_mov_b32_e32 v142, v130
	s_nop 1
	v_permlane32_swap_b32_e32 v130, v142
	v_add_f32_e32 v130, v130, v142
	v_mov_b32_e32 v142, v131
	s_nop 1
	v_permlane32_swap_b32_e32 v131, v142
	s_waitcnt lgkmcnt(1)
	v_add_f32_e32 v132, v132, v143
	s_waitcnt lgkmcnt(0)
	v_add_f32_e32 v133, v133, v144
	ds_swizzle_b32 v144, v140 offset:swizzle(SWAP,1)
	v_add_f32_e32 v131, v131, v142
	ds_swizzle_b32 v142, v133 offset:swizzle(SWAP,2)
	v_mov_b32_e32 v143, v132
	s_nop 1
	v_permlane32_swap_b32_e32 v132, v143
	v_add_f32_e32 v132, v132, v143
	ds_swizzle_b32 v143, v141 offset:swizzle(SWAP,1)
	s_waitcnt lgkmcnt(2)
	v_add_f32_e32 v140, v140, v144
	s_waitcnt lgkmcnt(1)
	v_add_f32_e32 v133, v133, v142
	ds_swizzle_b32 v144, v140 offset:swizzle(SWAP,2)
	ds_swizzle_b32 v142, v133 offset:swizzle(SWAP,4)
	s_waitcnt lgkmcnt(2)
	v_add_f32_e32 v141, v141, v143
	ds_swizzle_b32 v143, v141 offset:swizzle(SWAP,2)
	v_fmamk_f32 v87, v128, 0xba800000, v87
	s_waitcnt lgkmcnt(2)
	v_add_f32_e32 v140, v140, v144
	s_waitcnt lgkmcnt(1)
	v_add_f32_e32 v133, v133, v142
	ds_swizzle_b32 v144, v140 offset:swizzle(SWAP,4)
	ds_swizzle_b32 v142, v133 offset:swizzle(SWAP,8)
	s_waitcnt lgkmcnt(2)
	v_add_f32_e32 v141, v141, v143
	ds_swizzle_b32 v143, v141 offset:swizzle(SWAP,4)
	v_fmamk_f32 v85, v128, 0xba800000, v85
	s_waitcnt lgkmcnt(2)
	v_add_f32_e32 v140, v140, v144
	s_waitcnt lgkmcnt(1)
	v_add_f32_e32 v133, v133, v142
	ds_swizzle_b32 v144, v140 offset:swizzle(SWAP,8)
	ds_swizzle_b32 v142, v133 offset:swizzle(SWAP,16)
	s_waitcnt lgkmcnt(2)
	v_add_f32_e32 v141, v141, v143
	ds_swizzle_b32 v143, v141 offset:swizzle(SWAP,8)
	v_fmamk_f32 v86, v128, 0xba800000, v86
	s_waitcnt lgkmcnt(2)
	v_add_f32_e32 v140, v140, v144
	s_waitcnt lgkmcnt(1)
	v_add_f32_e32 v133, v133, v142
	ds_swizzle_b32 v144, v140 offset:swizzle(SWAP,16)
	v_mov_b32_e32 v142, v133
	s_nop 1
	v_permlane32_swap_b32_e32 v133, v142
	s_waitcnt lgkmcnt(1)
	v_add_f32_e32 v141, v141, v143
	v_add_f32_e32 v133, v133, v142
	ds_swizzle_b32 v142, v141 offset:swizzle(SWAP,16)
	s_waitcnt lgkmcnt(1)
	v_add_f32_e32 v140, v140, v144
	v_mov_b32_e32 v143, v140
	s_nop 1
	v_permlane32_swap_b32_e32 v140, v143
	v_add_f32_e32 v143, v140, v143
	s_waitcnt lgkmcnt(0)
	v_add_f32_e32 v140, v141, v142
	v_mov_b32_e32 v141, v140
	s_nop 1
	v_permlane32_swap_b32_e32 v140, v141
	v_add_f32_e32 v142, v140, v141
	v_fmac_f32_e32 v84, 0xba800000, v128
	v_mul_f32_e32 v140, v85, v85
	v_mul_f32_e32 v141, v87, v87
	v_fmac_f32_e32 v140, v84, v84
	v_fmac_f32_e32 v141, v86, v86
	v_fmamk_f32 v51, v128, 0xba800000, v51
	v_fmamk_f32 v49, v128, 0xba800000, v49
	v_add_f32_e32 v140, v140, v141
	v_fmamk_f32 v50, v128, 0xba800000, v50
	v_fmac_f32_e32 v48, 0xba800000, v128
	v_mul_f32_e32 v141, v49, v49
	v_mul_f32_e32 v144, v51, v51
	v_fmac_f32_e32 v141, v48, v48
	v_fmac_f32_e32 v144, v50, v50
	v_add_f32_e32 v141, v141, v144
	v_fmamk_f32 v23, v128, 0xba800000, v23
	v_fmamk_f32 v21, v128, 0xba800000, v21
	v_add_f32_e32 v140, v140, v141
	v_fmamk_f32 v22, v128, 0xba800000, v22
	v_fmac_f32_e32 v20, 0xba800000, v128
	v_mul_f32_e32 v141, v21, v21
	v_mul_f32_e32 v144, v23, v23
	v_fmac_f32_e32 v141, v20, v20
	v_fmac_f32_e32 v144, v22, v22
	v_add_f32_e32 v141, v141, v144
	v_fmamk_f32 v3, v128, 0xba800000, v3
	v_fmamk_f32 v1, v128, 0xba800000, v1
	v_add_f32_e32 v140, v141, v140
	v_fmamk_f32 v2, v128, 0xba800000, v2
	v_fmac_f32_e32 v0, 0xba800000, v128
	v_mul_f32_e32 v128, v1, v1
	v_mul_f32_e32 v141, v3, v3
	v_fmac_f32_e32 v128, v0, v0
	v_fmac_f32_e32 v141, v2, v2
	v_add_f32_e32 v128, v128, v141
	v_fmamk_f32 v95, v129, 0xba800000, v95
	v_fmamk_f32 v93, v129, 0xba800000, v93
	v_add_f32_e32 v128, v128, v140
	v_fmamk_f32 v94, v129, 0xba800000, v94
	v_fmac_f32_e32 v92, 0xba800000, v129
	v_mul_f32_e32 v140, v93, v93
	v_mul_f32_e32 v141, v95, v95
	v_fmac_f32_e32 v140, v92, v92
	v_fmac_f32_e32 v141, v94, v94
	v_fmamk_f32 v59, v129, 0xba800000, v59
	v_fmamk_f32 v57, v129, 0xba800000, v57
	v_add_f32_e32 v140, v140, v141
	v_fmamk_f32 v58, v129, 0xba800000, v58
	v_fmac_f32_e32 v56, 0xba800000, v129
	v_mul_f32_e32 v141, v57, v57
	v_mul_f32_e32 v144, v59, v59
	v_fmac_f32_e32 v141, v56, v56
	v_fmac_f32_e32 v144, v58, v58
	v_add_f32_e32 v141, v141, v144
	v_fmamk_f32 v31, v129, 0xba800000, v31
	v_fmamk_f32 v29, v129, 0xba800000, v29
	v_add_f32_e32 v140, v140, v141
	v_fmamk_f32 v30, v129, 0xba800000, v30
	v_fmac_f32_e32 v28, 0xba800000, v129
	v_mul_f32_e32 v141, v29, v29
	v_mul_f32_e32 v144, v31, v31
	v_fmac_f32_e32 v141, v28, v28
	v_fmac_f32_e32 v144, v30, v30
	v_add_f32_e32 v141, v141, v144
	v_fmamk_f32 v7, v129, 0xba800000, v7
	v_fmamk_f32 v5, v129, 0xba800000, v5
	v_add_f32_e32 v140, v141, v140
	v_fmamk_f32 v6, v129, 0xba800000, v6
	v_fmac_f32_e32 v4, 0xba800000, v129
	v_mul_f32_e32 v129, v5, v5
	v_mul_f32_e32 v141, v7, v7
	v_fmac_f32_e32 v129, v4, v4
	v_fmac_f32_e32 v141, v6, v6
	v_add_f32_e32 v129, v129, v141
	v_fmamk_f32 v103, v130, 0xba800000, v103
	v_fmamk_f32 v101, v130, 0xba800000, v101
	v_add_f32_e32 v129, v129, v140
	v_fmamk_f32 v102, v130, 0xba800000, v102
	v_fmac_f32_e32 v100, 0xba800000, v130
	v_mul_f32_e32 v140, v101, v101
	v_mul_f32_e32 v141, v103, v103
	v_fmac_f32_e32 v140, v100, v100
	v_fmac_f32_e32 v141, v102, v102
	v_fmamk_f32 v67, v130, 0xba800000, v67
	v_fmamk_f32 v65, v130, 0xba800000, v65
	v_add_f32_e32 v140, v140, v141
	v_fmamk_f32 v66, v130, 0xba800000, v66
	v_fmac_f32_e32 v64, 0xba800000, v130
	v_mul_f32_e32 v141, v65, v65
	v_mul_f32_e32 v144, v67, v67
	v_fmac_f32_e32 v141, v64, v64
	v_fmac_f32_e32 v144, v66, v66
	v_add_f32_e32 v141, v141, v144
	v_fmamk_f32 v39, v130, 0xba800000, v39
	v_fmamk_f32 v37, v130, 0xba800000, v37
	v_add_f32_e32 v140, v140, v141
	v_fmamk_f32 v38, v130, 0xba800000, v38
	v_fmac_f32_e32 v36, 0xba800000, v130
	v_mul_f32_e32 v141, v37, v37
	v_mul_f32_e32 v144, v39, v39
	v_fmac_f32_e32 v141, v36, v36
	v_fmac_f32_e32 v144, v38, v38
	v_add_f32_e32 v141, v141, v144
	v_fmamk_f32 v11, v130, 0xba800000, v11
	v_fmamk_f32 v9, v130, 0xba800000, v9
	v_add_f32_e32 v140, v141, v140
	v_fmamk_f32 v10, v130, 0xba800000, v10
	v_fmac_f32_e32 v8, 0xba800000, v130
	v_mul_f32_e32 v130, v9, v9
	v_mul_f32_e32 v141, v11, v11
	v_fmac_f32_e32 v130, v8, v8
	v_fmac_f32_e32 v141, v10, v10
	v_add_f32_e32 v130, v130, v141
	v_fmamk_f32 v111, v131, 0xba800000, v111
	v_fmamk_f32 v109, v131, 0xba800000, v109
	v_add_f32_e32 v130, v130, v140
	v_fmamk_f32 v110, v131, 0xba800000, v110
	v_fmac_f32_e32 v108, 0xba800000, v131
	v_mul_f32_e32 v140, v109, v109
	v_mul_f32_e32 v141, v111, v111
	v_fmac_f32_e32 v140, v108, v108
	v_fmac_f32_e32 v141, v110, v110
	v_fmamk_f32 v79, v131, 0xba800000, v79
	v_fmamk_f32 v77, v131, 0xba800000, v77
	v_add_f32_e32 v140, v140, v141
	v_fmamk_f32 v78, v131, 0xba800000, v78
	v_fmac_f32_e32 v76, 0xba800000, v131
	v_mul_f32_e32 v141, v77, v77
	v_mul_f32_e32 v144, v79, v79
	v_fmac_f32_e32 v141, v76, v76
	v_fmac_f32_e32 v144, v78, v78
	v_add_f32_e32 v141, v141, v144
	v_fmamk_f32 v47, v131, 0xba800000, v47
	v_fmamk_f32 v45, v131, 0xba800000, v45
	v_add_f32_e32 v140, v140, v141
	v_fmamk_f32 v46, v131, 0xba800000, v46
	v_fmac_f32_e32 v44, 0xba800000, v131
	v_mul_f32_e32 v141, v45, v45
	v_mul_f32_e32 v144, v47, v47
	v_fmac_f32_e32 v141, v44, v44
	v_fmac_f32_e32 v144, v46, v46
	v_add_f32_e32 v141, v141, v144
	v_fmamk_f32 v15, v131, 0xba800000, v15
	v_fmamk_f32 v13, v131, 0xba800000, v13
	v_add_f32_e32 v140, v141, v140
	v_fmamk_f32 v14, v131, 0xba800000, v14
	v_fmac_f32_e32 v12, 0xba800000, v131
	v_mul_f32_e32 v131, v13, v13
	v_mul_f32_e32 v141, v15, v15
	v_fmac_f32_e32 v131, v12, v12
	v_fmac_f32_e32 v141, v14, v14
	v_add_f32_e32 v131, v131, v141
	v_fmamk_f32 v115, v132, 0xba800000, v115
	v_fmamk_f32 v113, v132, 0xba800000, v113
	v_add_f32_e32 v131, v131, v140
	v_fmamk_f32 v114, v132, 0xba800000, v114
	v_fmac_f32_e32 v112, 0xba800000, v132
	v_mul_f32_e32 v140, v113, v113
	v_mul_f32_e32 v141, v115, v115
	v_fmac_f32_e32 v140, v112, v112
	v_fmac_f32_e32 v141, v114, v114
	v_fmamk_f32 v83, v132, 0xba800000, v83
	v_fmamk_f32 v81, v132, 0xba800000, v81
	v_add_f32_e32 v140, v140, v141
	v_fmamk_f32 v82, v132, 0xba800000, v82
	v_fmac_f32_e32 v80, 0xba800000, v132
	v_mul_f32_e32 v141, v81, v81
	v_mul_f32_e32 v144, v83, v83
	v_fmac_f32_e32 v141, v80, v80
	v_fmac_f32_e32 v144, v82, v82
	v_add_f32_e32 v141, v141, v144
	v_fmamk_f32 v55, v132, 0xba800000, v55
	v_fmamk_f32 v53, v132, 0xba800000, v53
	v_add_f32_e32 v140, v140, v141
	v_fmamk_f32 v54, v132, 0xba800000, v54
	v_fmac_f32_e32 v52, 0xba800000, v132
	v_mul_f32_e32 v141, v53, v53
	v_mul_f32_e32 v144, v55, v55
	v_fmac_f32_e32 v141, v52, v52
	v_fmac_f32_e32 v144, v54, v54
	v_add_f32_e32 v141, v141, v144
	v_fmamk_f32 v19, v132, 0xba800000, v19
	v_fmamk_f32 v17, v132, 0xba800000, v17
	v_add_f32_e32 v140, v141, v140
	v_fmamk_f32 v18, v132, 0xba800000, v18
	v_fmac_f32_e32 v16, 0xba800000, v132
	v_mul_f32_e32 v132, v17, v17
	v_mul_f32_e32 v141, v19, v19
	v_fmac_f32_e32 v132, v16, v16
	v_fmac_f32_e32 v141, v18, v18
	v_add_f32_e32 v132, v132, v141
	v_fmamk_f32 v141, v133, 0xba800000, v119
	v_fmamk_f32 v117, v133, 0xba800000, v117
	v_add_f32_e32 v132, v132, v140
	v_fmamk_f32 v140, v133, 0xba800000, v118
	v_fmac_f32_e32 v116, 0xba800000, v133
	v_mul_f32_e32 v118, v117, v117
	v_mul_f32_e32 v119, v141, v141
	v_fmac_f32_e32 v118, v116, v116
	v_fmac_f32_e32 v119, v140, v140
	v_fmamk_f32 v91, v133, 0xba800000, v91
	v_fmamk_f32 v89, v133, 0xba800000, v89
	v_add_f32_e32 v118, v118, v119
	v_fmamk_f32 v90, v133, 0xba800000, v90
	v_fmac_f32_e32 v88, 0xba800000, v133
	v_mul_f32_e32 v119, v89, v89
	v_mul_f32_e32 v144, v91, v91
	v_fmac_f32_e32 v119, v88, v88
	v_fmac_f32_e32 v144, v90, v90
	v_add_f32_e32 v119, v119, v144
	v_fmamk_f32 v63, v133, 0xba800000, v63
	v_fmamk_f32 v61, v133, 0xba800000, v61
	v_add_f32_e32 v118, v118, v119
	v_fmamk_f32 v62, v133, 0xba800000, v62
	v_fmac_f32_e32 v60, 0xba800000, v133
	v_mul_f32_e32 v119, v61, v61
	v_mul_f32_e32 v144, v63, v63
	v_fmac_f32_e32 v119, v60, v60
	v_fmac_f32_e32 v144, v62, v62
	v_add_f32_e32 v119, v119, v144
	v_fmamk_f32 v27, v133, 0xba800000, v27
	v_fmamk_f32 v25, v133, 0xba800000, v25
	v_add_f32_e32 v118, v119, v118
	v_fmamk_f32 v26, v133, 0xba800000, v26
	v_fmac_f32_e32 v24, 0xba800000, v133
	v_mul_f32_e32 v119, v25, v25
	v_mul_f32_e32 v133, v27, v27
	v_fmac_f32_e32 v119, v24, v24
	v_fmac_f32_e32 v133, v26, v26
	v_add_f32_e32 v119, v119, v133
	v_fmamk_f32 v153, v143, 0xba800000, v123
	v_fmamk_f32 v121, v143, 0xba800000, v121
	v_add_f32_e32 v118, v119, v118
	v_fmamk_f32 v152, v143, 0xba800000, v122
	v_fmac_f32_e32 v120, 0xba800000, v143
	v_mul_f32_e32 v119, v121, v121
	v_mul_f32_e32 v122, v153, v153
	v_fmac_f32_e32 v119, v120, v120
	v_fmac_f32_e32 v122, v152, v152
	v_fmamk_f32 v99, v143, 0xba800000, v99
	v_fmamk_f32 v97, v143, 0xba800000, v97
	v_add_f32_e32 v119, v119, v122
	v_fmamk_f32 v98, v143, 0xba800000, v98
	v_fmac_f32_e32 v96, 0xba800000, v143
	v_mul_f32_e32 v122, v97, v97
	v_mul_f32_e32 v123, v99, v99
	v_fmac_f32_e32 v122, v96, v96
	v_fmac_f32_e32 v123, v98, v98
	v_add_f32_e32 v122, v122, v123
	v_fmamk_f32 v71, v143, 0xba800000, v71
	v_fmamk_f32 v69, v143, 0xba800000, v69
	v_add_f32_e32 v119, v119, v122
	v_fmamk_f32 v70, v143, 0xba800000, v70
	v_fmac_f32_e32 v68, 0xba800000, v143
	v_mul_f32_e32 v122, v69, v69
	v_mul_f32_e32 v123, v71, v71
	v_fmac_f32_e32 v122, v68, v68
	v_fmac_f32_e32 v123, v70, v70
	v_add_f32_e32 v122, v122, v123
	v_fmamk_f32 v35, v143, 0xba800000, v35
	v_fmamk_f32 v33, v143, 0xba800000, v33
	v_add_f32_e32 v119, v122, v119
	v_fmamk_f32 v34, v143, 0xba800000, v34
	v_fmac_f32_e32 v32, 0xba800000, v143
	v_mul_f32_e32 v122, v33, v33
	v_mul_f32_e32 v123, v35, v35
	v_fmac_f32_e32 v122, v32, v32
	v_fmac_f32_e32 v123, v34, v34
	v_add_f32_e32 v122, v122, v123
	v_fmamk_f32 v155, v142, 0xba800000, v127
	v_fmamk_f32 v125, v142, 0xba800000, v125
	v_add_f32_e32 v119, v122, v119
	v_fmamk_f32 v154, v142, 0xba800000, v126
	v_fmac_f32_e32 v124, 0xba800000, v142
	v_mul_f32_e32 v122, v125, v125
	v_mul_f32_e32 v123, v155, v155
	v_fmac_f32_e32 v122, v124, v124
	v_fmac_f32_e32 v123, v154, v154
	v_fmamk_f32 v107, v142, 0xba800000, v107
	v_fmamk_f32 v105, v142, 0xba800000, v105
	v_add_f32_e32 v122, v122, v123
	v_fmamk_f32 v106, v142, 0xba800000, v106
	v_fmac_f32_e32 v104, 0xba800000, v142
	v_mul_f32_e32 v123, v105, v105
	v_mul_f32_e32 v126, v107, v107
	v_fmac_f32_e32 v123, v104, v104
	v_fmac_f32_e32 v126, v106, v106
	ds_swizzle_b32 v127, v128 offset:swizzle(SWAP,1)
	v_add_f32_e32 v123, v123, v126
	v_fmamk_f32 v75, v142, 0xba800000, v75
	v_fmamk_f32 v73, v142, 0xba800000, v73
	v_add_f32_e32 v122, v122, v123
	v_fmamk_f32 v74, v142, 0xba800000, v74
	v_fmac_f32_e32 v72, 0xba800000, v142
	v_mul_f32_e32 v123, v73, v73
	v_mul_f32_e32 v126, v75, v75
	v_fmac_f32_e32 v123, v72, v72
	v_fmac_f32_e32 v126, v74, v74
	v_add_f32_e32 v123, v123, v126
	v_add_f32_e32 v122, v123, v122
	s_waitcnt lgkmcnt(0)
	v_add_f32_e32 v123, v128, v127
	ds_swizzle_b32 v126, v123 offset:swizzle(SWAP,2)
	ds_swizzle_b32 v127, v129 offset:swizzle(SWAP,1)
	v_fmamk_f32 v43, v142, 0xba800000, v43
	v_fmamk_f32 v41, v142, 0xba800000, v41
	v_fmamk_f32 v42, v142, 0xba800000, v42
	s_waitcnt lgkmcnt(1)
	v_add_f32_e32 v123, v123, v126
	s_waitcnt lgkmcnt(0)
	v_add_f32_e32 v127, v129, v127
	ds_swizzle_b32 v126, v123 offset:swizzle(SWAP,4)
	ds_swizzle_b32 v129, v127 offset:swizzle(SWAP,2)
	v_fmac_f32_e32 v40, 0xba800000, v142
	v_mul_f32_e32 v128, v41, v41
	v_mul_f32_e32 v133, v43, v43
	s_waitcnt lgkmcnt(1)
	v_add_f32_e32 v123, v123, v126
	s_waitcnt lgkmcnt(0)
	v_add_f32_e32 v127, v127, v129
	ds_swizzle_b32 v126, v123 offset:swizzle(SWAP,8)
	ds_swizzle_b32 v129, v127 offset:swizzle(SWAP,4)
	v_fmac_f32_e32 v128, v40, v40
	v_fmac_f32_e32 v133, v42, v42
	v_add_f32_e32 v128, v128, v133
	s_waitcnt lgkmcnt(1)
	v_add_f32_e32 v123, v123, v126
	s_waitcnt lgkmcnt(0)
	v_add_f32_e32 v129, v127, v129
	ds_swizzle_b32 v126, v123 offset:swizzle(SWAP,16)
	ds_swizzle_b32 v133, v129 offset:swizzle(SWAP,8)
	v_add_f32_e32 v122, v128, v122
	ds_swizzle_b32 v128, v130 offset:swizzle(SWAP,1)
	s_andn2_b64 vcc, exec, s[16:17]
	s_waitcnt lgkmcnt(2)
	v_add_f32_e32 v126, v123, v126
	s_waitcnt lgkmcnt(1)
	v_add_f32_e32 v123, v129, v133
	ds_swizzle_b32 v129, v123 offset:swizzle(SWAP,16)
	s_waitcnt lgkmcnt(1)
	v_add_f32_e32 v128, v130, v128
	ds_swizzle_b32 v130, v128 offset:swizzle(SWAP,2)
	ds_swizzle_b32 v133, v131 offset:swizzle(SWAP,1)
	v_mov_b32_e32 v127, v126
	s_waitcnt lgkmcnt(2)
	v_add_f32_e32 v209, v123, v129
	v_mov_b32_e32 v211, v209
	s_waitcnt lgkmcnt(1)
	v_add_f32_e32 v123, v128, v130
	s_waitcnt lgkmcnt(0)
	v_add_f32_e32 v129, v131, v133
	ds_swizzle_b32 v128, v123 offset:swizzle(SWAP,4)
	ds_swizzle_b32 v130, v129 offset:swizzle(SWAP,2)
	ds_swizzle_b32 v131, v132 offset:swizzle(SWAP,1)
	v_permlane32_swap_b32_e32 v126, v127
	s_waitcnt lgkmcnt(2)
	v_add_f32_e32 v123, v123, v128
	s_waitcnt lgkmcnt(1)
	v_add_f32_e32 v129, v129, v130
	s_waitcnt lgkmcnt(0)
	v_add_f32_e32 v131, v132, v131
	ds_swizzle_b32 v128, v123 offset:swizzle(SWAP,8)
	ds_swizzle_b32 v130, v129 offset:swizzle(SWAP,4)
	ds_swizzle_b32 v132, v131 offset:swizzle(SWAP,2)
	v_permlane32_swap_b32_e32 v209, v211
	s_waitcnt lgkmcnt(2)
	v_add_f32_e32 v123, v123, v128
	s_waitcnt lgkmcnt(1)
	v_add_f32_e32 v129, v129, v130
	s_waitcnt lgkmcnt(0)
	v_add_f32_e32 v131, v131, v132
	ds_swizzle_b32 v128, v123 offset:swizzle(SWAP,16)
	ds_swizzle_b32 v130, v129 offset:swizzle(SWAP,8)
	ds_swizzle_b32 v132, v131 offset:swizzle(SWAP,4)
	s_waitcnt lgkmcnt(2)
	v_add_f32_e32 v213, v123, v128
	s_waitcnt lgkmcnt(1)
	v_add_f32_e32 v123, v129, v130
	s_waitcnt lgkmcnt(0)
	v_add_f32_e32 v129, v131, v132
	ds_swizzle_b32 v131, v118 offset:swizzle(SWAP,1)
	ds_swizzle_b32 v128, v123 offset:swizzle(SWAP,16)
	ds_swizzle_b32 v130, v129 offset:swizzle(SWAP,8)
	v_mov_b32_e32 v215, v213
	s_nop 1
	v_permlane32_swap_b32_e32 v213, v215
	s_waitcnt lgkmcnt(2)
	v_add_f32_e32 v118, v118, v131
	s_waitcnt lgkmcnt(1)
	v_add_f32_e32 v214, v123, v128
	s_waitcnt lgkmcnt(0)
	v_add_f32_e32 v123, v129, v130
	ds_swizzle_b32 v129, v118 offset:swizzle(SWAP,2)
	ds_swizzle_b32 v128, v123 offset:swizzle(SWAP,16)
	v_mov_b32_e32 v216, v214
	s_nop 1
	v_permlane32_swap_b32_e32 v214, v216
	s_waitcnt lgkmcnt(1)
	v_add_f32_e32 v118, v118, v129
	s_waitcnt lgkmcnt(0)
	v_add_f32_e32 v212, v123, v128
	ds_swizzle_b32 v123, v119 offset:swizzle(SWAP,1)
	ds_swizzle_b32 v128, v118 offset:swizzle(SWAP,4)
	ds_swizzle_b32 v129, v122 offset:swizzle(SWAP,1)
	v_mov_b32_e32 v217, v212
	s_nop 1
	v_permlane32_swap_b32_e32 v212, v217
	s_waitcnt lgkmcnt(2)
	v_add_f32_e32 v119, v119, v123
	s_waitcnt lgkmcnt(1)
	v_add_f32_e32 v118, v118, v128
	s_waitcnt lgkmcnt(0)
	v_add_f32_e32 v122, v122, v129
	ds_swizzle_b32 v123, v119 offset:swizzle(SWAP,2)
	ds_swizzle_b32 v128, v118 offset:swizzle(SWAP,8)
	ds_swizzle_b32 v129, v122 offset:swizzle(SWAP,2)
	s_waitcnt lgkmcnt(2)
	v_add_f32_e32 v119, v119, v123
	s_waitcnt lgkmcnt(1)
	v_add_f32_e32 v118, v118, v128
	s_waitcnt lgkmcnt(0)
	v_add_f32_e32 v122, v122, v129
	ds_swizzle_b32 v123, v119 offset:swizzle(SWAP,4)
	ds_swizzle_b32 v128, v118 offset:swizzle(SWAP,16)
	ds_swizzle_b32 v129, v122 offset:swizzle(SWAP,4)
	s_waitcnt lgkmcnt(2)
	v_add_f32_e32 v119, v119, v123
	s_waitcnt lgkmcnt(1)
	v_add_f32_e32 v210, v118, v128
	s_waitcnt lgkmcnt(0)
	v_add_f32_e32 v118, v122, v129
	ds_swizzle_b32 v123, v119 offset:swizzle(SWAP,8)
	ds_swizzle_b32 v122, v118 offset:swizzle(SWAP,8)
	v_mov_b32_e32 v218, v210
	s_nop 1
	v_permlane32_swap_b32_e32 v210, v218
	s_waitcnt lgkmcnt(1)
	v_add_f32_e32 v119, v119, v123
	s_waitcnt lgkmcnt(0)
	v_add_f32_e32 v118, v118, v122
	ds_swizzle_b32 v123, v119 offset:swizzle(SWAP,16)
	ds_swizzle_b32 v122, v118 offset:swizzle(SWAP,16)
	s_waitcnt lgkmcnt(1)
	v_add_f32_e32 v208, v119, v123
	s_waitcnt lgkmcnt(0)
	v_add_f32_e32 v190, v118, v122
	v_mov_b32_e32 v219, v208
	v_mov_b32_e32 v220, v190
	s_nop 0
	v_permlane32_swap_b32_e32 v208, v219
	v_permlane32_swap_b32_e32 v190, v220
	s_cbranch_vccnz .LBB0_1551
	s_movk_i32 s6, 0x8400
	s_mov_b32 s7, -1
	v_lshl_add_u64 v[192:193], v[138:139], 0, s[6:7]
	s_movk_i32 s6, 0x8800
	s_mov_b32 s7, -1
	v_lshl_add_u64 v[172:173], v[138:139], 0, s[6:7]
	s_movk_i32 s6, 0x8c00
	s_mov_b32 s7, -1
	v_lshl_add_u64 v[156:157], v[138:139], 0, s[6:7]
	s_movk_i32 s6, 0x9000
	s_mov_b32 s7, -1
	v_lshl_add_u64 v[118:119], v[138:139], 0, s[6:7]
	s_movk_i32 s6, 0x9400
	s_mov_b32 s7, -1
	v_lshl_add_u64 v[194:195], v[138:139], 0, s[6:7]
	s_movk_i32 s6, 0x9800
	s_mov_b32 s7, -1
	v_lshl_add_u64 v[174:175], v[138:139], 0, s[6:7]
	s_movk_i32 s6, 0x9c00
	s_mov_b32 s7, -1
	v_lshl_add_u64 v[158:159], v[138:139], 0, s[6:7]
	s_movk_i32 s6, 0xa000
	s_mov_b32 s7, -1
	v_lshl_add_u64 v[122:123], v[138:139], 0, s[6:7]
	s_movk_i32 s6, 0xa400
	s_mov_b32 s7, -1
	v_lshl_add_u64 v[198:199], v[138:139], 0, s[6:7]
	s_movk_i32 s6, 0xa800
	s_mov_b32 s7, -1
	v_lshl_add_u64 v[176:177], v[138:139], 0, s[6:7]
	s_movk_i32 s6, 0xac00
	s_mov_b32 s7, -1
	v_lshl_add_u64 v[160:161], v[138:139], 0, s[6:7]
	s_movk_i32 s6, 0xb000
	s_mov_b32 s7, -1
	v_lshl_add_u64 v[142:143], v[138:139], 0, s[6:7]
	s_movk_i32 s6, 0xb400
	s_mov_b32 s7, -1
	v_lshl_add_u64 v[200:201], v[138:139], 0, s[6:7]
	s_movk_i32 s6, 0xb800
	s_mov_b32 s7, -1
	v_lshl_add_u64 v[178:179], v[138:139], 0, s[6:7]
	s_movk_i32 s6, 0xbc00
	s_mov_b32 s7, -1
	v_lshl_add_u64 v[162:163], v[138:139], 0, s[6:7]
	s_movk_i32 s6, 0xc000
	s_mov_b32 s7, -1
	v_lshl_add_u64 v[144:145], v[138:139], 0, s[6:7]
	s_movk_i32 s6, 0xc400
	s_mov_b32 s7, -1
	v_lshl_add_u64 v[204:205], v[138:139], 0, s[6:7]
	s_movk_i32 s6, 0xc800
	s_mov_b32 s7, -1
	v_lshl_add_u64 v[182:183], v[138:139], 0, s[6:7]
	s_movk_i32 s6, 0xcc00
	s_mov_b32 s7, -1
	v_lshl_add_u64 v[166:167], v[138:139], 0, s[6:7]
	s_movk_i32 s6, 0xd000
	s_mov_b32 s7, -1
	v_lshl_add_u64 v[146:147], v[138:139], 0, s[6:7]
	s_movk_i32 s6, 0xd400
	s_mov_b32 s7, -1
	v_lshl_add_u64 v[206:207], v[138:139], 0, s[6:7]
	s_movk_i32 s6, 0xd800
	s_mov_b32 s7, -1
	v_lshl_add_u64 v[186:187], v[138:139], 0, s[6:7]
	s_movk_i32 s6, 0xdc00
	s_mov_b32 s7, -1
	v_lshl_add_u64 v[170:171], v[138:139], 0, s[6:7]
	s_movk_i32 s6, 0xe000
	s_mov_b32 s7, -1
	v_lshl_add_u64 v[150:151], v[138:139], 0, s[6:7]
	s_movk_i32 s6, 0xe400
	s_mov_b32 s7, -1
	v_lshl_add_u64 v[202:203], v[138:139], 0, s[6:7]
	s_movk_i32 s6, 0xe800
	s_mov_b32 s7, -1
	v_lshl_add_u64 v[184:185], v[138:139], 0, s[6:7]
	s_movk_i32 s6, 0xec00
	v_add_f32_e32 v126, v126, v127
	s_mov_b32 s7, -1
	v_fmamk_f32 v126, v126, 0x3a800000, v243
	v_lshl_add_u64 v[168:169], v[138:139], 0, s[6:7]
	s_movk_i32 s6, 0xf000
	v_cmp_gt_f32_e32 vcc, s84, v126
	v_mul_f32_e32 v127, 0x4f800000, v126
	s_mov_b32 s7, -1
	v_cndmask_b32_e32 v126, v126, v127, vcc
	v_lshl_add_u64 v[148:149], v[138:139], 0, s[6:7]
	s_movk_i32 s6, 0xf400
	v_sqrt_f32_e32 v127, v126
	s_mov_b32 s7, -1
	v_lshl_add_u64 v[196:197], v[138:139], 0, s[6:7]
	s_movk_i32 s6, 0xf800
	s_mov_b32 s7, -1
	v_lshl_add_u64 v[180:181], v[138:139], 0, s[6:7]
	s_movk_i32 s6, 0xfc00
	v_add_u32_e32 v128, -1, v127
	s_mov_b32 s7, -1
	v_fma_f32 v129, -v128, v127, v126
	v_lshl_add_u64 v[164:165], v[138:139], 0, s[6:7]
	v_cmp_ge_f32_e64 s[6:7], 0, v129
	v_add_u32_e32 v129, 1, v127
	v_add_f32_e32 v190, v190, v220
	v_cndmask_b32_e64 v128, v127, v128, s[6:7]
	v_fma_f32 v127, -v129, v127, v126
	v_cmp_lt_f32_e64 s[6:7], 0, v127
	v_fmamk_f32 v190, v190, 0x3a800000, v243
	v_mul_f32_e32 v220, 0x4f800000, v190
	v_cndmask_b32_e64 v127, v128, v129, s[6:7]
	v_mul_f32_e32 v128, 0x37800000, v127
	v_cndmask_b32_e32 v127, v127, v128, vcc
	v_cmp_class_f32_e32 vcc, v126, v248
	v_add_f32_e32 v208, v208, v219
	v_fmamk_f32 v208, v208, 0x3a800000, v243
	v_cndmask_b32_e32 v126, v127, v126, vcc
	v_div_scale_f32 v127, s[6:7], v126, v126, 1.0
	v_rcp_f32_e32 v128, v127
	v_mul_f32_e32 v219, 0x4f800000, v208
	v_add_f32_e32 v210, v210, v218
	v_fmamk_f32 v210, v210, 0x3a800000, v243
	v_fma_f32 v129, -v127, v128, 1.0
	v_fmac_f32_e32 v128, v129, v128
	v_div_scale_f32 v129, vcc, 1.0, v126, 1.0
	v_mul_f32_e32 v130, v129, v128
	v_fma_f32 v131, -v127, v130, v129
	v_fmac_f32_e32 v130, v131, v128
	v_fma_f32 v127, -v127, v130, v129
	v_div_fmas_f32 v127, v127, v128, v130
	v_cmp_gt_f32_e32 vcc, s84, v190
	v_mul_f32_e32 v218, 0x4f800000, v210
	v_add_f32_e32 v212, v212, v217
	v_cndmask_b32_e32 v190, v190, v220, vcc
	v_sqrt_f32_e32 v220, v190
	v_fmamk_f32 v212, v212, 0x3a800000, v243
	v_mul_f32_e32 v217, 0x4f800000, v212
	v_add_f32_e32 v214, v214, v216
	v_add_u32_e32 v221, -1, v220
	v_fma_f32 v222, -v221, v220, v190
	v_cmp_ge_f32_e64 s[6:7], 0, v222
	v_add_u32_e32 v222, 1, v220
	v_div_fixup_f32 v188, v127, v126, 1.0
	v_cndmask_b32_e64 v221, v220, v221, s[6:7]
	v_fma_f32 v220, -v222, v220, v190
	v_cmp_lt_f32_e64 s[6:7], 0, v220
	global_load_dwordx4 v[126:129], v[136:137], off
	global_load_dwordx4 v[130:133], v[134:135], off
	v_cndmask_b32_e64 v220, v221, v222, s[6:7]
	v_mul_f32_e32 v221, 0x37800000, v220
	v_cndmask_b32_e32 v220, v220, v221, vcc
	v_cmp_class_f32_e32 vcc, v190, v248
	v_fmamk_f32 v214, v214, 0x3a800000, v243
	v_mul_f32_e32 v216, 0x4f800000, v214
	v_cndmask_b32_e32 v190, v220, v190, vcc
	v_div_scale_f32 v220, s[6:7], v190, v190, 1.0
	v_rcp_f32_e32 v221, v220
	v_add_f32_e32 v213, v213, v215
	v_fmamk_f32 v213, v213, 0x3a800000, v243
	v_mul_f32_e32 v215, 0x4f800000, v213
	v_fma_f32 v222, -v220, v221, 1.0
	v_fmac_f32_e32 v221, v222, v221
	v_div_scale_f32 v222, vcc, 1.0, v190, 1.0
	v_mul_f32_e32 v223, v222, v221
	v_fma_f32 v224, -v220, v223, v222
	v_fmac_f32_e32 v223, v224, v221
	v_fma_f32 v220, -v220, v223, v222
	v_div_fmas_f32 v220, v220, v221, v223
	v_cmp_gt_f32_e32 vcc, s84, v208
	v_div_fixup_f32 v190, v220, v190, 1.0
	v_add_f32_e32 v209, v209, v211
	v_cndmask_b32_e32 v208, v208, v219, vcc
	v_sqrt_f32_e32 v219, v208
	v_fmamk_f32 v209, v209, 0x3a800000, v243
	v_mul_f32_e32 v211, 0x4f800000, v209
	v_pk_mul_f32 v[84:85], v[84:85], v[188:189] op_sel_hi:[1,0]
	v_add_u32_e32 v220, -1, v219
	v_fma_f32 v221, -v220, v219, v208
	v_cmp_ge_f32_e64 s[6:7], 0, v221
	v_add_u32_e32 v221, 1, v219
	v_pk_mul_f32 v[86:87], v[86:87], v[188:189] op_sel_hi:[1,0]
	v_cndmask_b32_e64 v220, v219, v220, s[6:7]
	v_fma_f32 v219, -v221, v219, v208
	v_cmp_lt_f32_e64 s[6:7], 0, v219
	v_pk_mul_f32 v[50:51], v[50:51], v[188:189] op_sel_hi:[1,0]
	v_pk_mul_f32 v[48:49], v[48:49], v[188:189] op_sel_hi:[1,0]
	v_cndmask_b32_e64 v219, v220, v221, s[6:7]
	v_mul_f32_e32 v220, 0x37800000, v219
	v_cndmask_b32_e32 v219, v219, v220, vcc
	v_cmp_class_f32_e32 vcc, v208, v248
	v_pk_mul_f32 v[22:23], v[22:23], v[188:189] op_sel_hi:[1,0]
	v_pk_mul_f32 v[20:21], v[20:21], v[188:189] op_sel_hi:[1,0]
	v_cndmask_b32_e32 v208, v219, v208, vcc
	v_div_scale_f32 v219, s[6:7], v208, v208, 1.0
	v_rcp_f32_e32 v220, v219
	v_pk_mul_f32 v[2:3], v[2:3], v[188:189] op_sel_hi:[1,0]
	v_pk_mul_f32 v[0:1], v[0:1], v[188:189] op_sel_hi:[1,0]
	v_fma_f32 v221, -v219, v220, 1.0
	v_fmac_f32_e32 v220, v221, v220
	v_div_scale_f32 v221, vcc, 1.0, v208, 1.0
	v_mul_f32_e32 v222, v221, v220
	v_fma_f32 v223, -v219, v222, v221
	v_fmac_f32_e32 v222, v223, v220
	v_fma_f32 v219, -v219, v222, v221
	v_div_fmas_f32 v219, v219, v220, v222
	v_cmp_gt_f32_e32 vcc, s84, v210
	v_div_fixup_f32 v208, v219, v208, 1.0
	s_waitcnt vmcnt(0) lgkmcnt(0)
	v_pk_fma_f32 v[86:87], v[86:87], v[132:133], v[128:129]
	v_cndmask_b32_e32 v210, v210, v218, vcc
	v_sqrt_f32_e32 v218, v210
	v_pk_fma_f32 v[84:85], v[84:85], v[130:131], v[126:127]
	global_store_dwordx4 v[192:193], v[84:87], off
	v_add_u32_e32 v219, -1, v218
	v_fma_f32 v220, -v219, v218, v210
	v_cmp_ge_f32_e64 s[6:7], 0, v220
	v_add_u32_e32 v220, 1, v218
	s_nop 0
	v_cndmask_b32_e64 v219, v218, v219, s[6:7]
	v_fma_f32 v218, -v220, v218, v210
	v_cmp_lt_f32_e64 s[6:7], 0, v218
	s_nop 1
	v_cndmask_b32_e64 v218, v219, v220, s[6:7]
	v_mul_f32_e32 v219, 0x37800000, v218
	v_cndmask_b32_e32 v218, v218, v219, vcc
	v_cmp_class_f32_e32 vcc, v210, v248
	s_nop 1
	v_cndmask_b32_e32 v210, v218, v210, vcc
	v_div_scale_f32 v218, s[6:7], v210, v210, 1.0
	v_rcp_f32_e32 v219, v218
	s_nop 0
	v_fma_f32 v220, -v218, v219, 1.0
	v_fmac_f32_e32 v219, v220, v219
	v_div_scale_f32 v220, vcc, 1.0, v210, 1.0
	v_mul_f32_e32 v221, v220, v219
	v_fma_f32 v222, -v218, v221, v220
	v_fmac_f32_e32 v221, v222, v219
	v_fma_f32 v218, -v218, v221, v220
	v_div_fmas_f32 v218, v218, v219, v221
	v_cmp_gt_f32_e32 vcc, s84, v212
	v_div_fixup_f32 v210, v218, v210, 1.0
	s_nop 0
	v_cndmask_b32_e32 v212, v212, v217, vcc
	v_sqrt_f32_e32 v217, v212
	s_nop 0
	v_add_u32_e32 v218, -1, v217
	v_fma_f32 v219, -v218, v217, v212
	v_cmp_ge_f32_e64 s[6:7], 0, v219
	v_add_u32_e32 v219, 1, v217
	s_nop 0
	v_cndmask_b32_e64 v218, v217, v218, s[6:7]
	v_fma_f32 v217, -v219, v217, v212
	v_cmp_lt_f32_e64 s[6:7], 0, v217
	s_nop 1
	v_cndmask_b32_e64 v217, v218, v219, s[6:7]
	v_mul_f32_e32 v218, 0x37800000, v217
	v_cndmask_b32_e32 v217, v217, v218, vcc
	v_cmp_class_f32_e32 vcc, v212, v248
	s_nop 1
	v_cndmask_b32_e32 v212, v217, v212, vcc
	v_div_scale_f32 v217, s[6:7], v212, v212, 1.0
	v_rcp_f32_e32 v218, v217
	s_nop 0
	v_fma_f32 v219, -v217, v218, 1.0
	v_fmac_f32_e32 v218, v219, v218
	v_div_scale_f32 v219, vcc, 1.0, v212, 1.0
	v_mul_f32_e32 v220, v219, v218
	v_fma_f32 v221, -v217, v220, v219
	v_fmac_f32_e32 v220, v221, v218
	v_fma_f32 v217, -v217, v220, v219
	v_div_fmas_f32 v217, v217, v218, v220
	v_cmp_gt_f32_e32 vcc, s84, v214
	v_div_fixup_f32 v212, v217, v212, 1.0
	s_nop 0
	v_cndmask_b32_e32 v214, v214, v216, vcc
	v_sqrt_f32_e32 v216, v214
	s_nop 0
	v_add_u32_e32 v217, -1, v216
	v_fma_f32 v218, -v217, v216, v214
	v_cmp_ge_f32_e64 s[6:7], 0, v218
	v_add_u32_e32 v218, 1, v216
	s_nop 0
	v_cndmask_b32_e64 v217, v216, v217, s[6:7]
	v_fma_f32 v216, -v218, v216, v214
	v_cmp_lt_f32_e64 s[6:7], 0, v216
	s_nop 1
	v_cndmask_b32_e64 v216, v217, v218, s[6:7]
	v_mul_f32_e32 v217, 0x37800000, v216
	v_cndmask_b32_e32 v216, v216, v217, vcc
	v_cmp_class_f32_e32 vcc, v214, v248
	s_nop 1
	v_cndmask_b32_e32 v214, v216, v214, vcc
	v_div_scale_f32 v216, s[6:7], v214, v214, 1.0
	v_rcp_f32_e32 v217, v216
	s_nop 0
	v_fma_f32 v218, -v216, v217, 1.0
	v_fmac_f32_e32 v217, v218, v217
	v_div_scale_f32 v218, vcc, 1.0, v214, 1.0
	v_mul_f32_e32 v219, v218, v217
	v_fma_f32 v220, -v216, v219, v218
	v_fmac_f32_e32 v219, v220, v217
	v_fma_f32 v216, -v216, v219, v218
	v_div_fmas_f32 v216, v216, v217, v219
	v_cmp_gt_f32_e32 vcc, s84, v213
	v_div_fixup_f32 v214, v216, v214, 1.0
	s_nop 0
	v_cndmask_b32_e32 v213, v213, v215, vcc
	v_sqrt_f32_e32 v215, v213
	s_nop 0
	v_add_u32_e32 v216, -1, v215
	v_fma_f32 v217, -v216, v215, v213
	v_cmp_ge_f32_e64 s[6:7], 0, v217
	v_add_u32_e32 v217, 1, v215
	s_nop 0
	v_cndmask_b32_e64 v216, v215, v216, s[6:7]
	v_fma_f32 v215, -v217, v215, v213
	v_cmp_lt_f32_e64 s[6:7], 0, v215
	s_nop 1
	v_cndmask_b32_e64 v215, v216, v217, s[6:7]
	v_mul_f32_e32 v216, 0x37800000, v215
	v_cndmask_b32_e32 v215, v215, v216, vcc
	v_cmp_class_f32_e32 vcc, v213, v248
	s_nop 1
	v_cndmask_b32_e32 v213, v215, v213, vcc
	v_div_scale_f32 v215, s[6:7], v213, v213, 1.0
	v_rcp_f32_e32 v216, v215
	s_nop 0
	v_fma_f32 v217, -v215, v216, 1.0
	v_fmac_f32_e32 v216, v217, v216
	v_div_scale_f32 v217, vcc, 1.0, v213, 1.0
	v_mul_f32_e32 v218, v217, v216
	v_fma_f32 v219, -v215, v218, v217
	v_fmac_f32_e32 v218, v219, v216
	v_fma_f32 v215, -v215, v218, v217
	v_div_fmas_f32 v215, v215, v216, v218
	v_cmp_gt_f32_e32 vcc, s84, v209
	v_div_fixup_f32 v216, v215, v213, 1.0
	s_nop 0
	v_cndmask_b32_e32 v209, v209, v211, vcc
	v_sqrt_f32_e32 v211, v209
	s_nop 0
	v_add_u32_e32 v213, -1, v211
	v_fma_f32 v215, -v213, v211, v209
	v_cmp_ge_f32_e64 s[6:7], 0, v215
	v_add_u32_e32 v215, 1, v211
	s_nop 0
	v_cndmask_b32_e64 v213, v211, v213, s[6:7]
	v_fma_f32 v211, -v215, v211, v209
	v_cmp_lt_f32_e64 s[6:7], 0, v211
	s_nop 1
	v_cndmask_b32_e64 v211, v213, v215, s[6:7]
	v_mul_f32_e32 v213, 0x37800000, v211
	v_cndmask_b32_e32 v211, v211, v213, vcc
	v_cmp_class_f32_e32 vcc, v209, v248
	s_nop 1
	v_cndmask_b32_e32 v209, v211, v209, vcc
	v_div_scale_f32 v211, s[6:7], v209, v209, 1.0
	v_rcp_f32_e32 v213, v211
	s_nop 0
	v_fma_f32 v215, -v211, v213, 1.0
	v_fmac_f32_e32 v213, v215, v213
	v_div_scale_f32 v215, vcc, 1.0, v209, 1.0
	v_mul_f32_e32 v217, v215, v213
	v_fma_f32 v218, -v211, v217, v215
	v_fmac_f32_e32 v217, v218, v213
	v_fma_f32 v211, -v211, v217, v215
	v_div_fmas_f32 v211, v211, v213, v217
	v_div_fixup_f32 v218, v211, v209, 1.0
	v_pk_mul_f32 v[84:85], v[92:93], v[218:219] op_sel_hi:[1,0]
	v_pk_mul_f32 v[86:87], v[94:95], v[218:219] op_sel_hi:[1,0]
	v_pk_fma_f32 v[84:85], v[84:85], v[130:131], v[126:127]
	v_pk_fma_f32 v[86:87], v[86:87], v[132:133], v[128:129]
	global_store_dwordx4 v[194:195], v[84:87], off
	s_nop 1
	v_pk_mul_f32 v[84:85], v[100:101], v[216:217] op_sel_hi:[1,0]
	v_pk_mul_f32 v[86:87], v[102:103], v[216:217] op_sel_hi:[1,0]
	v_pk_fma_f32 v[84:85], v[84:85], v[130:131], v[126:127]
	v_pk_fma_f32 v[86:87], v[86:87], v[132:133], v[128:129]
	global_store_dwordx4 v[198:199], v[84:87], off
	s_nop 1
	v_pk_mul_f32 v[84:85], v[108:109], v[214:215] op_sel_hi:[1,0]
	v_pk_mul_f32 v[86:87], v[110:111], v[214:215] op_sel_hi:[1,0]
	v_pk_fma_f32 v[84:85], v[84:85], v[130:131], v[126:127]
	v_pk_fma_f32 v[86:87], v[86:87], v[132:133], v[128:129]
	global_store_dwordx4 v[200:201], v[84:87], off
	s_nop 1
	v_pk_mul_f32 v[84:85], v[112:113], v[212:213] op_sel_hi:[1,0]
	v_pk_mul_f32 v[86:87], v[114:115], v[212:213] op_sel_hi:[1,0]
	v_pk_fma_f32 v[84:85], v[84:85], v[130:131], v[126:127]
	v_pk_fma_f32 v[86:87], v[86:87], v[132:133], v[128:129]
	global_store_dwordx4 v[204:205], v[84:87], off
	s_nop 1
	v_pk_mul_f32 v[84:85], v[116:117], v[210:211] op_sel_hi:[1,0]
	v_pk_mul_f32 v[86:87], v[140:141], v[210:211] op_sel_hi:[1,0]
	v_pk_fma_f32 v[84:85], v[84:85], v[130:131], v[126:127]
	v_pk_fma_f32 v[86:87], v[86:87], v[132:133], v[128:129]
	global_store_dwordx4 v[206:207], v[84:87], off
	s_nop 1
	v_pk_mul_f32 v[84:85], v[120:121], v[208:209] op_sel_hi:[1,0]
	v_pk_mul_f32 v[86:87], v[152:153], v[208:209] op_sel_hi:[1,0]
	v_pk_fma_f32 v[84:85], v[130:131], v[84:85], v[126:127]
	v_pk_fma_f32 v[86:87], v[132:133], v[86:87], v[128:129]
	global_store_dwordx4 v[202:203], v[84:87], off
	s_nop 1
	v_pk_mul_f32 v[84:85], v[124:125], v[190:191] op_sel_hi:[1,0]
	v_pk_mul_f32 v[86:87], v[154:155], v[190:191] op_sel_hi:[1,0]
	v_pk_fma_f32 v[84:85], v[130:131], v[84:85], v[126:127]
	v_pk_fma_f32 v[86:87], v[132:133], v[86:87], v[128:129]
	global_store_dwordx4 v[196:197], v[84:87], off
	global_load_dwordx4 v[84:87], v[134:135], off offset:1024
	s_nop 0
	global_load_dwordx4 v[92:95], v[136:137], off offset:1024
	s_waitcnt vmcnt(0) lgkmcnt(0)
	v_pk_fma_f32 v[48:49], v[48:49], v[84:85], v[92:93]
	v_pk_fma_f32 v[50:51], v[50:51], v[86:87], v[94:95]
	global_store_dwordx4 v[172:173], v[48:51], off
	s_nop 1
	v_pk_mul_f32 v[50:51], v[58:59], v[218:219] op_sel_hi:[1,0]
	v_pk_mul_f32 v[48:49], v[56:57], v[218:219] op_sel_hi:[1,0]
	v_pk_fma_f32 v[50:51], v[50:51], v[86:87], v[94:95]
	v_pk_fma_f32 v[48:49], v[48:49], v[84:85], v[92:93]
	global_store_dwordx4 v[174:175], v[48:51], off
	s_nop 1
	v_pk_mul_f32 v[50:51], v[66:67], v[216:217] op_sel_hi:[1,0]
	v_pk_mul_f32 v[48:49], v[64:65], v[216:217] op_sel_hi:[1,0]
	v_pk_fma_f32 v[50:51], v[50:51], v[86:87], v[94:95]
	v_pk_fma_f32 v[48:49], v[48:49], v[84:85], v[92:93]
	global_store_dwordx4 v[176:177], v[48:51], off
	s_nop 1
	v_pk_mul_f32 v[50:51], v[78:79], v[214:215] op_sel_hi:[1,0]
	v_pk_mul_f32 v[48:49], v[76:77], v[214:215] op_sel_hi:[1,0]
	v_pk_fma_f32 v[50:51], v[50:51], v[86:87], v[94:95]
	v_pk_fma_f32 v[48:49], v[48:49], v[84:85], v[92:93]
	global_store_dwordx4 v[178:179], v[48:51], off
	s_nop 1
	v_pk_mul_f32 v[50:51], v[82:83], v[212:213] op_sel_hi:[1,0]
	v_pk_mul_f32 v[48:49], v[80:81], v[212:213] op_sel_hi:[1,0]
	v_pk_fma_f32 v[50:51], v[50:51], v[86:87], v[94:95]
	v_pk_fma_f32 v[48:49], v[48:49], v[84:85], v[92:93]
	global_store_dwordx4 v[182:183], v[48:51], off
	s_nop 1
	v_pk_mul_f32 v[50:51], v[90:91], v[210:211] op_sel_hi:[1,0]
	v_pk_mul_f32 v[48:49], v[88:89], v[210:211] op_sel_hi:[1,0]
	v_pk_fma_f32 v[50:51], v[50:51], v[86:87], v[94:95]
	v_pk_fma_f32 v[48:49], v[48:49], v[84:85], v[92:93]
	global_store_dwordx4 v[186:187], v[48:51], off
	s_nop 1
	v_pk_mul_f32 v[50:51], v[98:99], v[208:209] op_sel_hi:[1,0]
	v_pk_mul_f32 v[48:49], v[96:97], v[208:209] op_sel_hi:[1,0]
	v_pk_fma_f32 v[50:51], v[50:51], v[86:87], v[94:95]
	v_pk_fma_f32 v[48:49], v[48:49], v[84:85], v[92:93]
	global_store_dwordx4 v[184:185], v[48:51], off
	s_nop 1
	v_pk_mul_f32 v[50:51], v[106:107], v[190:191] op_sel_hi:[1,0]
	v_pk_mul_f32 v[48:49], v[104:105], v[190:191] op_sel_hi:[1,0]
	v_pk_fma_f32 v[50:51], v[50:51], v[86:87], v[94:95]
	v_pk_fma_f32 v[48:49], v[48:49], v[84:85], v[92:93]
	global_store_dwordx4 v[180:181], v[48:51], off
	global_load_dwordx4 v[48:51], v[134:135], off offset:2048
	s_nop 0
	global_load_dwordx4 v[56:59], v[136:137], off offset:2048
	s_waitcnt vmcnt(0) lgkmcnt(0)
	v_pk_fma_f32 v[20:21], v[20:21], v[48:49], v[56:57]
	v_pk_fma_f32 v[22:23], v[22:23], v[50:51], v[58:59]
	global_store_dwordx4 v[156:157], v[20:23], off
	s_nop 1
	v_pk_mul_f32 v[22:23], v[30:31], v[218:219] op_sel_hi:[1,0]
	v_pk_mul_f32 v[20:21], v[28:29], v[218:219] op_sel_hi:[1,0]
	v_pk_fma_f32 v[22:23], v[22:23], v[50:51], v[58:59]
	v_pk_fma_f32 v[20:21], v[20:21], v[48:49], v[56:57]
	global_store_dwordx4 v[158:159], v[20:23], off
	s_nop 1
	v_pk_mul_f32 v[22:23], v[38:39], v[216:217] op_sel_hi:[1,0]
	v_pk_mul_f32 v[20:21], v[36:37], v[216:217] op_sel_hi:[1,0]
	v_pk_fma_f32 v[22:23], v[22:23], v[50:51], v[58:59]
	v_pk_fma_f32 v[20:21], v[20:21], v[48:49], v[56:57]
	global_store_dwordx4 v[160:161], v[20:23], off
	s_nop 1
	v_pk_mul_f32 v[22:23], v[46:47], v[214:215] op_sel_hi:[1,0]
	v_pk_mul_f32 v[20:21], v[44:45], v[214:215] op_sel_hi:[1,0]
	v_pk_fma_f32 v[22:23], v[22:23], v[50:51], v[58:59]
	v_pk_fma_f32 v[20:21], v[20:21], v[48:49], v[56:57]
	global_store_dwordx4 v[162:163], v[20:23], off
	s_nop 1
	v_pk_mul_f32 v[22:23], v[54:55], v[212:213] op_sel_hi:[1,0]
	v_pk_mul_f32 v[20:21], v[52:53], v[212:213] op_sel_hi:[1,0]
	v_pk_fma_f32 v[22:23], v[22:23], v[50:51], v[58:59]
	v_pk_fma_f32 v[20:21], v[20:21], v[48:49], v[56:57]
	global_store_dwordx4 v[166:167], v[20:23], off
	s_nop 1
	v_pk_mul_f32 v[22:23], v[62:63], v[210:211] op_sel_hi:[1,0]
	v_pk_mul_f32 v[20:21], v[60:61], v[210:211] op_sel_hi:[1,0]
	v_pk_fma_f32 v[22:23], v[22:23], v[50:51], v[58:59]
	v_pk_fma_f32 v[20:21], v[20:21], v[48:49], v[56:57]
	global_store_dwordx4 v[170:171], v[20:23], off
	s_nop 1
	v_pk_mul_f32 v[22:23], v[70:71], v[208:209] op_sel_hi:[1,0]
	v_pk_mul_f32 v[20:21], v[68:69], v[208:209] op_sel_hi:[1,0]
	v_pk_fma_f32 v[22:23], v[22:23], v[50:51], v[58:59]
	v_pk_fma_f32 v[20:21], v[20:21], v[48:49], v[56:57]
	global_store_dwordx4 v[168:169], v[20:23], off
	s_nop 1
	v_pk_mul_f32 v[22:23], v[74:75], v[190:191] op_sel_hi:[1,0]
	v_pk_mul_f32 v[20:21], v[72:73], v[190:191] op_sel_hi:[1,0]
	v_pk_fma_f32 v[22:23], v[22:23], v[50:51], v[58:59]
	v_pk_fma_f32 v[20:21], v[20:21], v[48:49], v[56:57]
	global_store_dwordx4 v[164:165], v[20:23], off
	global_load_dwordx4 v[20:23], v[134:135], off offset:3072
	s_nop 0
	global_load_dwordx4 v[28:31], v[136:137], off offset:3072
	s_waitcnt vmcnt(0) lgkmcnt(0)
	v_pk_fma_f32 v[0:1], v[0:1], v[20:21], v[28:29]
	v_pk_fma_f32 v[2:3], v[2:3], v[22:23], v[30:31]
	global_store_dwordx4 v[118:119], v[0:3], off
	s_nop 1
	v_pk_mul_f32 v[2:3], v[6:7], v[218:219] op_sel_hi:[1,0]
	v_pk_mul_f32 v[0:1], v[4:5], v[218:219] op_sel_hi:[1,0]
	v_pk_fma_f32 v[2:3], v[2:3], v[22:23], v[30:31]
	v_pk_fma_f32 v[0:1], v[0:1], v[20:21], v[28:29]
	global_store_dwordx4 v[122:123], v[0:3], off
	s_nop 1
	v_pk_mul_f32 v[2:3], v[10:11], v[216:217] op_sel_hi:[1,0]
	v_pk_mul_f32 v[0:1], v[8:9], v[216:217] op_sel_hi:[1,0]
	v_pk_fma_f32 v[2:3], v[2:3], v[22:23], v[30:31]
	v_pk_fma_f32 v[0:1], v[0:1], v[20:21], v[28:29]
	global_store_dwordx4 v[142:143], v[0:3], off
	s_nop 1
	v_pk_mul_f32 v[2:3], v[14:15], v[214:215] op_sel_hi:[1,0]
	v_pk_mul_f32 v[0:1], v[12:13], v[214:215] op_sel_hi:[1,0]
	v_pk_fma_f32 v[2:3], v[2:3], v[22:23], v[30:31]
	v_pk_fma_f32 v[0:1], v[0:1], v[20:21], v[28:29]
	global_store_dwordx4 v[144:145], v[0:3], off
	s_nop 1
	v_pk_mul_f32 v[2:3], v[18:19], v[212:213] op_sel_hi:[1,0]
	v_pk_mul_f32 v[0:1], v[16:17], v[212:213] op_sel_hi:[1,0]
	v_pk_fma_f32 v[2:3], v[2:3], v[22:23], v[30:31]
	v_pk_fma_f32 v[0:1], v[0:1], v[20:21], v[28:29]
	global_store_dwordx4 v[146:147], v[0:3], off
	s_nop 1
	v_pk_mul_f32 v[2:3], v[26:27], v[210:211] op_sel_hi:[1,0]
	v_pk_mul_f32 v[0:1], v[24:25], v[210:211] op_sel_hi:[1,0]
	v_pk_fma_f32 v[2:3], v[2:3], v[22:23], v[30:31]
	v_pk_fma_f32 v[0:1], v[0:1], v[20:21], v[28:29]
	global_store_dwordx4 v[150:151], v[0:3], off
	s_nop 1
	v_pk_mul_f32 v[2:3], v[34:35], v[208:209] op_sel_hi:[1,0]
	v_pk_mul_f32 v[0:1], v[32:33], v[208:209] op_sel_hi:[1,0]
	v_pk_fma_f32 v[2:3], v[2:3], v[22:23], v[30:31]
	v_pk_fma_f32 v[0:1], v[0:1], v[20:21], v[28:29]
	global_store_dwordx4 v[148:149], v[0:3], off
	s_nop 1
	v_pk_mul_f32 v[2:3], v[42:43], v[190:191] op_sel_hi:[1,0]
	v_pk_mul_f32 v[0:1], v[40:41], v[190:191] op_sel_hi:[1,0]
	v_pk_fma_f32 v[2:3], v[2:3], v[22:23], v[30:31]
	v_pk_fma_f32 v[0:1], v[0:1], v[20:21], v[28:29]
	global_store_dwordx4 v[138:139], v[0:3], off
	s_branch .LBB0_1551
